# conv pass: raw-row prefetch made two items deep (second register set, rows requested after the weight waits so they are not drained by in-order vmcnt waits)
# speedup vs baseline: 1.0211x; 1.0199x over previous
; __device__ __forceinline__ void conv_fetch(const bf16_t* raw, int item, int tid, u32x4 (&rg)[3]) {
;     constexpr int NFB = 80;
;     const int ch = item / NFB, fb = item % NFB;
;     const bool is_ctx = ch < (CGR / 128);
;     const long row0 = (long)ch * 128;
; #pragma unroll
;     for (int i = 0; i < 3; ++i) {
;         const int idx = tid + 512 * i;
;         rg[i] = (u32x4){0u, 0u, 0u, 0u};
;         if (idx < 134 * 8) { const int ir = idx >> 3, c8 = idx & 7; int tok; bool ok;
;             if (is_ctx) { tok = ir - 2; const int gt = (ch & 1) * 128 + tok; ok = (ir < 131) && gt >= 0 && gt < 256; }
;             else { const int sg = ir >= 67 ? 1 : 0, q = ir - 67 * sg; tok = 64 * sg + q - 2; ok = q >= 2 && q < 66; }
;             if (ok) rg[i] = *(const u32x4*)(raw + (size_t)(row0 + tok) * NA + fb * 64 + c8 * 8); }
;     }
; __device__ __forceinline__ void phase_conv(const Params& p, LAS unsigned char* lds, int wg, int G, int tid) {
;     ...
;     u32x4 rg[3];
;     int item = wg, buf = 0;
;     if (item < NIT) conv_fetch(raw, item, tid, rg);
.LBB0_625:
	s_andn2_b64 vcc, exec, s[4:5]
	s_cbranch_vccnz .LBB0_674
	v_lshlrev_b32_e32 v12, 3, v240
	v_and_b32_e32 v50, 56, v12
	v_lshlrev_b32_e32 v192, 1, v50
	v_lshl_add_u64 v[20:21], s[0:1], 0, v[192:193]
	s_movk_i32 s0, 0x430
	v_cmp_gt_i32_e64 s[2:3], s0, v240
	v_ashrrev_i32_e32 v13, 3, v240
	s_movk_i32 s0, 0x42
	v_cmp_lt_i32_e32 vcc, s0, v13
	v_mov_b32_e32 v17, 0xffffffbd
	v_add_u32_e32 v51, -2, v13
	v_cndmask_b32_e32 v14, 0, v17, vcc
	s_movk_i32 s1, 0x83
	v_cndmask_b32_e64 v15, 0, 64, vcc
	v_add_u32_e32 v14, v14, v51
	v_cmp_gt_i32_e64 s[6:7], s1, v13
	v_add_u32_e32 v13, 0x200, v240
	v_add_u32_e32 v52, v14, v15
	v_cmp_gt_u32_e64 s[4:5], 64, v14
	v_ashrrev_i32_e32 v14, 3, v13
	v_cmp_lt_i32_e32 vcc, s0, v14
	v_add_u32_e32 v53, -2, v14
	v_cmp_gt_i32_e64 s[12:13], s1, v14
	v_cndmask_b32_e32 v15, 0, v17, vcc
	v_cndmask_b32_e64 v16, 0, 64, vcc
	v_add_u32_e32 v15, v15, v53
	v_add_u32_e32 v14, 0x400, v240
	v_add_u32_e32 v54, v15, v16
	v_cmp_gt_u32_e64 s[10:11], 64, v15
	v_ashrrev_i32_e32 v15, 3, v14
	v_cmp_lt_i32_e32 vcc, s0, v15
	v_add_u32_e32 v55, -2, v15
	v_cmp_gt_i32_e64 s[18:19], s1, v15
	v_cndmask_b32_e32 v16, 0, v17, vcc
	v_cndmask_b32_e64 v17, 0, 64, vcc
	v_add_u32_e32 v16, v16, v55
	v_add_u32_e32 v56, v16, v17
	v_cmp_gt_u32_e64 s[16:17], 64, v16
	v_ashrrev_i32_e32 v16, 2, v240
	v_lshrrev_b32_e32 v15, 8, v240
	v_and_b32_e32 v22, -8, v16
	v_and_b32_e32 v16, 56, v16
	s_movk_i32 s0, 0x43
	v_readlane_b32 s20, v255, 31
	v_mad_u32_u24 v59, v15, s0, v16
	v_readlane_b32 s21, v255, 32
	s_add_u32 s0, s20, 0x1000
	s_addc_u32 s1, s21, 0
	s_add_u32 s24, s20, 0x2000
	s_addc_u32 s25, s21, 0
	s_mov_b32 s93, s88
	s_mov_b32 s88, s26
	s_mov_b64 s[96:97], s[38:39]
	s_add_u32 s26, s20, 0x3000
	v_readlane_b32 s36, v255, 19
	s_addc_u32 s27, s21, 0
	v_readlane_b32 s38, v255, 21
	v_readlane_b32 s39, v255, 22
	s_add_u32 s28, s38, 0x4000
	s_addc_u32 s29, s39, 0
	s_add_u32 s30, s38, 0x8000
	v_and_b32_e32 v60, 0xffffffc0, v12
	v_lshlrev_b32_e32 v12, 3, v13
	s_addc_u32 s31, s39, 0
	s_movk_i32 s8, 0x230
	v_and_b32_e32 v57, 31, v245
	v_ashrrev_i32_e32 v23, 31, v22
	v_and_b32_e32 v61, 0xffffffc0, v12
	v_lshlrev_b32_e32 v12, 3, v14
	v_readlane_b32 s37, v255, 20
	v_readlane_b32 s41, v255, 24
	s_add_u32 s36, s38, 0xc000
	s_mov_b64 s[72:73], s[84:85]
	s_mov_b64 s[68:69], s[86:87]
	s_mov_b32 s54, s76
	s_mov_b64 s[76:77], s[60:61]
	s_mov_b64 s[60:61], s[44:45]
	s_mov_b32 s33, 0
	v_cmp_gt_i32_e64 s[8:9], s8, v240
	v_cmp_gt_i32_e64 s[14:15], 48, v240
	v_lshlrev_b32_e32 v58, 1, v57
	v_and_b32_e32 v62, 0xffffffc0, v12
	s_addc_u32 s37, s39, 0
	v_lshlrev_b64 v[24:25], 11, v[22:23]
	s_lshl_b32 s38, s92, 6
	s_lshl_b32 s39, s34, 6
	s_mov_b32 s41, s92
	v_readlane_b32 s22, v255, 33
	v_readlane_b32 s23, v255, 34
	v_readlane_b32 s40, v255, 23
	v_readlane_b32 s42, v255, 25
	v_readlane_b32 s43, v255, 26
	s_add_i32 s40, s41, s34
	s_mul_hi_i32 s20, s40, 0x66666667
	s_lshr_b32 s21, s20, 31
	s_ashr_i32 s20, s20, 5
	s_add_i32 s20, s20, s21
	s_cmpk_lt_i32 s40, 0xa00
	s_cselect_b64 vcc, -1, 0
	s_ashr_i32 s21, s20, 31
	s_lshl_b64 s[22:23], s[20:21], 7
	s_lshl_b32 s21, s20, 7
	s_and_b32 s45, s21, 0x80
	s_mulk_i32 s20, 0xec00
	s_add_i32 s21, s39, s38
	s_add_i32 s20, s21, s20
	s_ashr_i32 s21, s20, 31
	v_lshl_add_u64 v[66:67], s[20:21], 1, v[20:21]
	v_mov_b32_e32 v72, 0
	v_mov_b32_e32 v68, 0
	v_mov_b32_e32 v69, 0
	v_mov_b32_e32 v70, 0
	v_mov_b32_e32 v71, 0
	s_and_saveexec_b64 s[48:49], s[2:3]
	s_cbranch_execz .Lconv_p_637
	v_add_u32_e32 v68, s45, v51
	s_movk_i32 s20, 0x100
	v_cmp_gt_u32_e64 s[20:21], s20, v68
	s_and_b64 s[20:21], s[6:7], s[20:21]
	v_cndmask_b32_e64 v69, 0, 1, s[4:5]
	v_cndmask_b32_e64 v68, 0, 1, s[20:21]
	v_cndmask_b32_e32 v68, v69, v68, vcc
	v_and_b32_e32 v68, 1, v68
	v_cmp_eq_u32_e64 s[20:21], 1, v68
	v_mov_b32_e32 v71, 0
	v_mov_b32_e32 v70, 0
	v_mov_b32_e32 v69, 0
	v_mov_b32_e32 v68, 0
	s_and_saveexec_b64 s[50:51], s[20:21]
	s_cbranch_execz .Lconv_p_636
	v_cndmask_b32_e32 v68, v52, v51, vcc
	v_ashrrev_i32_e32 v69, 31, v68
	v_lshl_add_u64 v[68:69], s[22:23], 0, v[68:69]
	v_mad_u64_u32 v[70:71], s[20:21], v68, s78, v[66:67]
	v_mad_i32_i24 v71, v69, s78, v71
	global_load_dwordx4 v[68:71], v[70:71], off

; __device__ __forceinline__ void conv_fetch(const bf16_t* raw, int item, int tid, u32x4 (&rg)[3]) {
;     ...
;     for (int i = 0; i < 3; ++i) {
;         const int idx = tid + 512 * i;
;         rg[i] = (u32x4){0u, 0u, 0u, 0u};
;         if (idx < 134 * 8) { const int ir = idx >> 3, c8 = idx & 7; int tok; bool ok;
;             if (is_ctx) { tok = ir - 2; const int gt = (ch & 1) * 128 + tok; ok = (ir < 131) && gt >= 0 && gt < 256; }
;             else { const int sg = ir >= 67 ? 1 : 0, q = ir - 67 * sg; tok = 64 * sg + q - 2; ok = q >= 2 && q < 66; }
;             if (ok) rg[i] = *(const u32x4*)(raw + (size_t)(row0 + tok) * NA + fb * 64 + c8 * 8); }
;     }
.Lconv_p_637:
	s_or_b64 exec, exec, s[48:49]
	v_mov_b32_e32 v73, 0
	v_mov_b32_e32 v74, 0
	v_mov_b32_e32 v75, 0
	s_and_saveexec_b64 s[48:49], s[8:9]
	s_cbranch_execz .Lconv_p_641
	v_add_u32_e32 v72, s45, v53
	s_movk_i32 s20, 0x100
	v_cmp_gt_u32_e64 s[20:21], s20, v72
	s_and_b64 s[20:21], s[12:13], s[20:21]
	v_cndmask_b32_e64 v73, 0, 1, s[10:11]
	v_cndmask_b32_e64 v72, 0, 1, s[20:21]
	v_cndmask_b32_e32 v72, v73, v72, vcc
	v_and_b32_e32 v72, 1, v72
	v_cmp_eq_u32_e64 s[20:21], 1, v72
	v_mov_b32_e32 v75, 0
	v_mov_b32_e32 v74, 0
	v_mov_b32_e32 v73, 0
	v_mov_b32_e32 v72, 0
	s_and_saveexec_b64 s[50:51], s[20:21]
	s_cbranch_execz .Lconv_p_640
	v_cndmask_b32_e32 v72, v54, v53, vcc
	v_ashrrev_i32_e32 v73, 31, v72
	v_lshl_add_u64 v[72:73], s[22:23], 0, v[72:73]
	v_mad_u64_u32 v[74:75], s[20:21], v72, s78, v[66:67]
	v_mad_i32_i24 v75, v73, s78, v75
	global_load_dwordx4 v[72:75], v[74:75], off

; __device__ __forceinline__ void conv_fetch(const bf16_t* raw, int item, int tid, u32x4 (&rg)[3]) {
;     ...
;     for (int i = 0; i < 3; ++i) {
;         const int idx = tid + 512 * i;
;         rg[i] = (u32x4){0u, 0u, 0u, 0u};
;         if (idx < 134 * 8) { const int ir = idx >> 3, c8 = idx & 7; int tok; bool ok;
;             if (is_ctx) { tok = ir - 2; const int gt = (ch & 1) * 128 + tok; ok = (ir < 131) && gt >= 0 && gt < 256; }
;             else { const int sg = ir >= 67 ? 1 : 0, q = ir - 67 * sg; tok = 64 * sg + q - 2; ok = q >= 2 && q < 66; }
;             if (ok) rg[i] = *(const u32x4*)(raw + (size_t)(row0 + tok) * NA + fb * 64 + c8 * 8); }
;     }
.Lconv_p_641:
	s_or_b64 exec, exec, s[48:49]
	v_mov_b32_e32 v79, 0
	v_mov_b32_e32 v78, 0
	v_mov_b32_e32 v77, 0
	v_mov_b32_e32 v76, 0
	s_and_saveexec_b64 s[48:49], s[14:15]
	s_cbranch_execz .Lconv_p_645
	v_add_u32_e32 v76, s45, v55
	s_movk_i32 s20, 0x100
	v_cmp_gt_u32_e64 s[20:21], s20, v76
	s_and_b64 s[20:21], s[18:19], s[20:21]
	v_cndmask_b32_e64 v77, 0, 1, s[16:17]
	v_cndmask_b32_e64 v76, 0, 1, s[20:21]
	v_cndmask_b32_e32 v76, v77, v76, vcc
	v_and_b32_e32 v76, 1, v76
	v_cmp_eq_u32_e64 s[20:21], 1, v76
	v_mov_b32_e32 v79, 0
	v_mov_b32_e32 v78, 0
	v_mov_b32_e32 v77, 0
	v_mov_b32_e32 v76, 0
	s_and_saveexec_b64 s[50:51], s[20:21]
	s_cbranch_execz .Lconv_p_644
	v_cndmask_b32_e32 v76, v56, v55, vcc
	v_ashrrev_i32_e32 v77, 31, v76
	v_lshl_add_u64 v[76:77], s[22:23], 0, v[76:77]
	v_mad_u64_u32 v[78:79], s[20:21], v76, s78, v[66:67]
	v_mad_i32_i24 v79, v77, s78, v79
	global_load_dwordx4 v[76:79], v[78:79], off

; __device__ __forceinline__ void phase_conv(const Params& p, LAS unsigned char* lds, int wg, int G, int tid) {
;     ...
;     u32x4 rg[3];
;     int item = wg, buf = 0;
;     if (item < NIT) conv_fetch(raw, item, tid, rg);
;     for (; item < NIT; item += G) {
.Lconv_p_645:
	s_or_b64 exec, exec, s[48:49]
	s_waitcnt vmcnt(0)
	s_branch .LBB0_628

; #define LAS __attribute__((address_space(3)))
; __device__ __forceinline__ float bflo(unsigned w) { return __uint_as_float(w << 16); }
; __device__ __forceinline__ float bfhi(unsigned w) { return __uint_as_float(w & 0xffff0000u); }
; __device__ __forceinline__ void phase_conv(const Params& p, LAS unsigned char* lds, int wg, int G, int tid) {
;     ...
;     for (; item < NIT; item += G) {
;         LAS float* tile = (LAS float*)(lds + buf * 34816);
; #pragma unroll
;         for (int i = 0; i < 3; ++i) { const int idx = tid + 512 * i;
;             if (idx < 134 * 8) { LAS float* d = tile + (idx >> 3) * 64 + (idx & 7) * 8; const u32x4 w = rg[i];
;                 *(LAS f32x4*)d = (f32x4){bflo(w.x), bfhi(w.x), bflo(w.y), bfhi(w.y)}; *(LAS f32x4*)(d + 4) = (f32x4){bflo(w.z), bfhi(w.z), bflo(w.w), bfhi(w.w)}; } }
;         __syncthreads();
;         if (item + G < NIT) conv_fetch(raw, item + G, tid, rg);
.LBB0_631:
	v_lshl_add_u32 v16, v62, 2, v12
	v_lshlrev_b32_e32 v12, 16, v8
	v_and_b32_e32 v13, 0xffff0000, v8
	v_lshlrev_b32_e32 v14, 16, v9
	v_and_b32_e32 v15, 0xffff0000, v9
	ds_write_b128 v16, v[12:15]
	v_lshlrev_b32_e32 v12, 16, v10
	v_and_b32_e32 v13, 0xffff0000, v10
	v_lshlrev_b32_e32 v14, 16, v11
	v_and_b32_e32 v15, 0xffff0000, v11
	ds_write_b128 v16, v[12:15] offset:16
.LBB0_632:
	s_or_b64 exec, exec, s[20:21]
	s_add_i32 s40, s41, s34
	s_cmpk_gt_i32 s40, 0x59ff
	s_cselect_b64 s[42:43], -1, 0
	s_and_b64 vcc, exec, s[42:43]
	s_waitcnt lgkmcnt(0)
	s_barrier

; #define LAS __attribute__((address_space(3)))
; __device__ __forceinline__ void conv_fetch(const bf16_t* raw, int item, int tid, u32x4 (&rg)[3]) {
;     ...
;     for (int i = 0; i < 3; ++i) {
;         const int idx = tid + 512 * i;
;         rg[i] = (u32x4){0u, 0u, 0u, 0u};
;         if (idx < 134 * 8) { const int ir = idx >> 3, c8 = idx & 7; int tok; bool ok;
;             if (is_ctx) { tok = ir - 2; const int gt = (ch & 1) * 128 + tok; ok = (ir < 131) && gt >= 0 && gt < 256; }
;             else { const int sg = ir >= 67 ? 1 : 0, q = ir - 67 * sg; tok = 64 * sg + q - 2; ok = q >= 2 && q < 66; }
;             if (ok) rg[i] = *(const u32x4*)(raw + (size_t)(row0 + tok) * NA + fb * 64 + c8 * 8); }
; __device__ __forceinline__ void phase_conv(const Params& p, LAS unsigned char* lds, int wg, int G, int tid) {
;     ...
;         if (item + G < NIT) conv_fetch(raw, item + G, tid, rg);
;         const int ch = item / NFB, fb = item % NFB;
;         const size_t row0 = (size_t)ch * 128;
;         const int fp = tid & 31, tq = tid >> 5;
;         const int feat = fb * 64 + 2 * fp;
;         f32x2 w0, w1, w2, w3, bias;
;         if (feat < 4096) { w0 = *(const f32x2*)(p.ssd_conv_w + feat); w1 = *(const f32x2*)(p.ssd_conv_w + 4096 + feat); w2 = *(const f32x2*)(p.ssd_conv_w + 8192 + feat); w3 = *(const f32x2*)(p.ssd_conv_w + 12288 + feat); bias = *(const f32x2*)(p.ssd_conv_b + feat); }
;         else { const int lf = feat - 4096; w0 = *(const f32x2*)(p.lru_conv_w + lf); w1 = *(const f32x2*)(p.lru_conv_w + 1024 + lf); w2 = *(const f32x2*)(p.lru_conv_w + 2048 + lf); w3 = *(const f32x2*)(p.lru_conv_w + 3072 + lf); bias = *(const f32x2*)(p.lru_conv_b + lf); }
;         const bool is_ctx = ch < (CGR / 128);
;         const bool act = fb < 64;
;         f32x2 o[8];
;         const int ib0 = is_ctx ? tq * 8 : (tq >> 3) * 67 + (tq & 7) * 8;
;         const LAS f32x2* tp = (const LAS f32x2*)tile + fp;
;         f32x2 v0 = tp[(ib0 + 0) * 32], v1 = tp[(ib0 + 1) * 32], v2 = tp[(ib0 + 2) * 32];
; #pragma unroll
;         for (int k = 0; k < 8; ++k) {
;             const f32x2 v3 = tp[(ib0 + k + 3) * 32];
;             f32x2 a = bias + w0 * v0 + w1 * v1 + w2 * v2 + w3 * v3;
.LBB0_650:
	s_or_b64 exec, exec, s[20:21]
	global_load_dwordx2 v[30:31], v[12:13], off
	global_load_dwordx2 v[32:33], v[28:29], off
	global_load_dwordx2 v[38:39], v[14:15], off
	global_load_dwordx2 v[36:37], v[16:17], off
	global_load_dwordx2 v[34:35], v[18:19], off
	s_mul_i32 s20, s48, 0xffffffb0
	s_add_i32 s45, s41, s20
	s_cmpk_lt_i32 s41, 0xa00
	s_cselect_b64 s[20:21], -1, 0
	v_cndmask_b32_e64 v12, v59, v22, s[20:21]
	v_lshl_add_u32 v13, v57, 3, s44
	v_lshlrev_b32_e32 v12, 8, v12
	v_add_u32_e32 v27, v13, v12
	ds_read2_b64 v[16:19], v27 offset1:32
	ds_read2_b64 v[12:15], v27 offset0:64 offset1:96
	s_cmp_lt_i32 s45, 64
	s_cselect_b64 s[50:51], -1, 0
	s_cmp_gt_i32 s45, 63
	s_waitcnt vmcnt(3) lgkmcnt(1)
	v_pk_fma_f32 v[16:17], v[30:31], v[16:17], v[32:33]
	s_waitcnt vmcnt(2)
	v_pk_fma_f32 v[16:17], v[38:39], v[18:19], v[16:17]
	s_waitcnt vmcnt(1) lgkmcnt(0)
	v_pk_fma_f32 v[16:17], v[36:37], v[12:13], v[16:17]
	s_waitcnt vmcnt(0)
	v_pk_fma_f32 v[16:17], v[34:35], v[14:15], v[16:17]
	v_mov_b32_e32 v0, v68
	v_mov_b32_e32 v1, v69
	v_mov_b32_e32 v2, v70
	v_mov_b32_e32 v3, v71
	v_mov_b32_e32 v4, v72
	v_mov_b32_e32 v5, v73
	v_mov_b32_e32 v6, v74
	v_mov_b32_e32 v7, v75
	v_mov_b32_e32 v8, v76
	v_mov_b32_e32 v9, v77
	v_mov_b32_e32 v10, v78
	v_mov_b32_e32 v11, v79
	s_mov_b32 s101, s45
	v_writelane_b32 v255, s48, 63
	v_writelane_b32 v255, s50, 59
	v_writelane_b32 v255, s51, 60
	v_writelane_b32 v255, s20, 61
	v_writelane_b32 v255, s21, 62
	s_add_i32 s100, s40, s34
	s_cmpk_gt_i32 s100, 0x59ff
	s_cbranch_scc1 .Lconv_nopf
	s_mul_hi_i32 s20, s100, 0x66666667
	s_lshr_b32 s21, s20, 31
	s_ashr_i32 s20, s20, 5
	s_add_i32 s20, s20, s21
	s_cmpk_lt_i32 s100, 0xa00
	s_cselect_b64 vcc, -1, 0
	s_ashr_i32 s21, s20, 31
	s_lshl_b64 s[22:23], s[20:21], 7
	s_lshl_b32 s21, s20, 7
	s_and_b32 s45, s21, 0x80
	s_mulk_i32 s20, 0xec00
	s_add_i32 s21, s39, s38
	s_add_i32 s21, s21, s39
	s_add_i32 s20, s21, s20
	s_ashr_i32 s21, s20, 31
	v_lshl_add_u64 v[66:67], s[20:21], 1, v[20:21]
	v_mov_b32_e32 v72, 0
	v_mov_b32_e32 v68, 0
	v_mov_b32_e32 v69, 0
	v_mov_b32_e32 v70, 0
	v_mov_b32_e32 v71, 0
	s_and_saveexec_b64 s[48:49], s[2:3]
	s_cbranch_execz .Lconv_l_637
	v_add_u32_e32 v68, s45, v51
	s_movk_i32 s20, 0x100
	v_cmp_gt_u32_e64 s[20:21], s20, v68
	s_and_b64 s[20:21], s[6:7], s[20:21]
	v_cndmask_b32_e64 v69, 0, 1, s[4:5]
	v_cndmask_b32_e64 v68, 0, 1, s[20:21]
	v_cndmask_b32_e32 v68, v69, v68, vcc
	v_and_b32_e32 v68, 1, v68
	v_cmp_eq_u32_e64 s[20:21], 1, v68
	v_mov_b32_e32 v71, 0
	v_mov_b32_e32 v70, 0
	v_mov_b32_e32 v69, 0
	v_mov_b32_e32 v68, 0
	s_and_saveexec_b64 s[50:51], s[20:21]
	s_cbranch_execz .Lconv_l_636
	v_cndmask_b32_e32 v68, v52, v51, vcc
	v_ashrrev_i32_e32 v69, 31, v68
	v_lshl_add_u64 v[68:69], s[22:23], 0, v[68:69]
	v_mad_u64_u32 v[70:71], s[20:21], v68, s78, v[66:67]
	v_mad_i32_i24 v71, v69, s78, v71
	global_load_dwordx4 v[68:71], v[70:71], off

; __device__ __forceinline__ void phase_conv(const Params& p, LAS unsigned char* lds, int wg, int G, int tid) {
;     ...
;         for (int k = 0; k < 8; ++k) {
;             const f32x2 v3 = tp[(ib0 + k + 3) * 32];
;             f32x2 a = bias + w0 * v0 + w1 * v1 + w2 * v2 + w3 * v3;
;             if (act) { f32x2 d; d.x = 1.f + __expf(-a.x); d.y = 1.f + __expf(-a.y); f32x2 rc; rc.x = __builtin_amdgcn_rcpf(d.x); rc.y = __builtin_amdgcn_rcpf(d.y); a = a * rc; }
;             o[k] = a;
.Lconv_nopf:
	v_readlane_b32 s50, v255, 59
	v_readlane_b32 s51, v255, 60
	v_readlane_b32 s20, v255, 61
	v_readlane_b32 s21, v255, 62
	v_readlane_b32 s48, v255, 63
	s_mov_b32 s45, s101
	s_nop 3
	s_cmp_gt_i32 s45, 63
	s_cbranch_scc1 .LBB0_652
	v_mul_f32_e32 v28, 0xbfb8aa3b, v16
	v_mul_f32_e32 v29, 0xbfb8aa3b, v17
	v_exp_f32_e32 v28, v28
	v_exp_f32_e32 v29, v29
	v_add_f32_e32 v28, 1.0, v28
	v_add_f32_e32 v29, 1.0, v29
	v_rcp_f32_e32 v28, v28
	v_rcp_f32_e32 v29, v29
	s_nop 0
	v_pk_mul_f32 v[16:17], v[16:17], v[28:29]

; #define LAS __attribute__((address_space(3)))
; __device__ __forceinline__ float bflo(unsigned w) { return __uint_as_float(w << 16); }
; __device__ __forceinline__ float bfhi(unsigned w) { return __uint_as_float(w & 0xffff0000u); }
; __device__ __forceinline__ void phase_conv(const Params& p, LAS unsigned char* lds, int wg, int G, int tid) {
;     ...
;     for (; item < NIT; item += G) {
;         LAS float* tile = (LAS float*)(lds + buf * 34816);
; #pragma unroll
;         for (int i = 0; i < 3; ++i) { const int idx = tid + 512 * i;
;             if (idx < 134 * 8) { LAS float* d = tile + (idx >> 3) * 64 + (idx & 7) * 8; const u32x4 w = rg[i];
;                 *(LAS f32x4*)d = (f32x4){bflo(w.x), bfhi(w.x), bflo(w.y), bfhi(w.y)}; *(LAS f32x4*)(d + 4) = (f32x4){bflo(w.z), bfhi(w.z), bflo(w.w), bfhi(w.w)}; } }
.LBB0_671:
	v_lshl_add_u32 v13, v60, 2, v12
	v_lshlrev_b32_e32 v14, 16, v0
	v_and_b32_e32 v15, 0xffff0000, v0
	v_lshlrev_b32_e32 v16, 16, v1
	v_and_b32_e32 v17, 0xffff0000, v1
	ds_write_b128 v13, v[14:17]
	v_lshlrev_b32_e32 v14, 16, v2
	v_and_b32_e32 v15, 0xffff0000, v2
	v_lshlrev_b32_e32 v16, 16, v3
	v_and_b32_e32 v17, 0xffff0000, v3
	ds_write_b128 v13, v[14:17] offset:16
	s_or_b64 exec, exec, s[20:21]
	s_and_saveexec_b64 s[20:21], s[8:9]
	s_cbranch_execz .LBB0_630
.LBB0_672:
	v_lshl_add_u32 v13, v61, 2, v12
	v_lshlrev_b32_e32 v14, 16, v4
	v_and_b32_e32 v15, 0xffff0000, v4
	v_lshlrev_b32_e32 v16, 16, v5
	v_and_b32_e32 v17, 0xffff0000, v5
	ds_write_b128 v13, v[14:17]
	v_lshlrev_b32_e32 v14, 16, v6
	v_and_b32_e32 v15, 0xffff0000, v6
	v_lshlrev_b32_e32 v16, 16, v7
	v_and_b32_e32 v17, 0xffff0000, v7
	ds_write_b128 v13, v[14:17] offset:16
	s_or_b64 exec, exec, s[20:21]
	s_and_saveexec_b64 s[20:21], s[14:15]
	s_cbranch_execnz .LBB0_631
	s_branch .LBB0_632
